# stack f + gqa attention: first half-step's tile staging DMA issued inside the next score tile's MFMA sequence instead of right behind the barrier
# baseline (speedup 1.0000x reference)
; #define SBAR() __builtin_amdgcn_sched_barrier(0)
; template <int D0> __device__ __forceinline__ void pv_one(f32x16& od, int vb, bf16x8 pa0, bf16x8 pa1, bf16x8 pa2, bf16x8 pa3) {
;     const s16x4 l0 = tr_read<v_rd_off(D0, 0, 0)>(vb), h0 = tr_read<v_rd_off(D0, 0, 1)>(vb), l1 = tr_read<v_rd_off(D0, 1, 0)>(vb), h1 = tr_read<v_rd_off(D0, 1, 1)>(vb);
;     const s16x4 l2 = tr_read<v_rd_off(D0, 2, 0)>(vb), h2 = tr_read<v_rd_off(D0, 2, 1)>(vb), l3 = tr_read<v_rd_off(D0, 3, 0)>(vb), h3 = tr_read<v_rd_off(D0, 3, 1)>(vb);
;     asm volatile("s_waitcnt lgkmcnt(0)" ::: "memory"); SBAR();
;     ...
;     od = __builtin_amdgcn_mfma_f32_32x32x16_bf16(pa0, PK(l0, h0), od, 0, 0, 0);
;     od = __builtin_amdgcn_mfma_f32_32x32x16_bf16(pa1, PK(l1, h1), od, 0, 0, 0);
;     od = __builtin_amdgcn_mfma_f32_32x32x16_bf16(pa2, PK(l2, h2), od, 0, 0, 0);
;     od = __builtin_amdgcn_mfma_f32_32x32x16_bf16(pa3, PK(l3, h3), od, 0, 0, 0);
;     ...
; }
; __device__ __forceinline__ void pv_d0(f32x16* o, int vb, bf16x8 pa0, bf16x8 pa1, bf16x8 pa2, bf16x8 pa3) {
; __device__ __forceinline__ void finishSM(f32x16& p0, f32x16& p1, float alpha, float& l_reg, bf16x8& pa0, bf16x8& pa1, bf16x8& pa2, bf16x8& pa3) {
; #pragma unroll
;     for (int r = 0; r < 16; ++r) p1[r] = __builtin_amdgcn_exp2f(p1[r]);
;     float ps = 0;
; #pragma unroll
;     for (int r = 0; r < 16; ++r) ps += p0[r];
; #pragma unroll
;     for (int r = 0; r < 16; ++r) ps += p1[r];
;     { auto rr = __builtin_amdgcn_permlane32_swap(__float_as_uint(ps), __float_as_uint(ps), false, false);
;       ps = __uint_as_float(rr[0]) + __uint_as_float(rr[1]); }
;     l_reg = l_reg * alpha + ps;
;     ...
;     PK4(p0, 0, pa0); PK4(p0, 8, pa1); PK4(p1, 0, pa2); PK4(p1, 8, pa3);
;     ...
; }
; template <int DQK> __device__ __forceinline__ void qkt(f32x16& p0, f32x16& p1, const char* Ks, const bf16x8* qr, int r32, int hi) {
;     p0 = f32x16{}; p1 = f32x16{};
; #pragma unroll
;     for (int d0 = 0; d0 < DQK / 16; ++d0) { const int cb = (d0 * 16 + hi * 8) * 2;
;         const bf16x8 b0 = *reinterpret_cast<const bf16x8*>(Ks + kswz<DQK>(r32, cb));
;         const bf16x8 b1 = *reinterpret_cast<const bf16x8*>(Ks + kswz<DQK>(32 + r32, cb));
;         p0 = __builtin_amdgcn_mfma_f32_32x32x16_bf16(b0, qr[d0], p0, 0, 0, 0);
;         p1 = __builtin_amdgcn_mfma_f32_32x32x16_bf16(b1, qr[d0], p1, 0, 0, 0); }
; }
.LBB0_3449:
	s_mov_b32 s24, s25
	s_lshl_b32 s25, s7, 14
	s_add_i32 s14, s25, 0
	v_add_u32_e32 v68, s14, v169
	ds_read_b128 v[64:67], v68 offset:49152
	ds_read_b128 v[68:71], v68 offset:57344
	v_add_u32_e32 v158, s14, v171
	ds_read_b128 v[220:223], v158 offset:49152
	ds_read_b128 v[228:231], v158 offset:57344
	v_add_u32_e32 v158, s14, v170
	ds_read_b128 v[236:239], v158 offset:49152
	ds_read_b128 v[240:243], v158 offset:57344
	s_waitcnt lgkmcnt(4)
	v_mfma_f32_32x32x16_bf16 v[80:95], v[64:67], v[124:127], 0
	v_exp_f32_e32 v152, v152
	v_exp_f32_e32 v153, v153
	v_exp_f32_e32 v150, v150
	v_exp_f32_e32 v151, v151
	v_exp_f32_e32 v148, v148
	v_exp_f32_e32 v149, v149
	v_exp_f32_e32 v194, v147
	v_mfma_f32_32x32x16_bf16 v[64:79], v[68:71], v[124:127], 0
	v_exp_f32_e32 v195, v144
	v_exp_f32_e32 v227, v129
	v_cvt_pk_bf16_f32 v129, v207, v210
	v_cvt_pk_bf16_f32 v144, v196, v198
	v_cvt_pk_bf16_f32 v147, v150, v151
	s_waitcnt lgkmcnt(2)
	v_mfma_f32_32x32x16_bf16 v[80:95], v[220:223], v[120:123], v[80:95]
	v_mfma_f32_32x32x16_bf16 v[64:79], v[228:231], v[120:123], v[64:79]
	v_add_u32_e32 v158, s14, v168
	ds_read_b128 v[220:223], v158 offset:49152
	ds_read_b128 v[228:231], v158 offset:57344
	s_waitcnt lgkmcnt(2)
	v_mfma_f32_32x32x16_bf16 v[80:95], v[236:239], v[116:119], v[80:95]
	v_mfma_f32_32x32x16_bf16 v[64:79], v[240:243], v[116:119], v[64:79]
	v_add_u32_e32 v158, s14, v167
	ds_read_b128 v[236:239], v158 offset:49152
	ds_read_b128 v[240:243], v158 offset:57344
	s_waitcnt lgkmcnt(2)
	v_mfma_f32_32x32x16_bf16 v[80:95], v[220:223], v[112:115], v[80:95]
	v_mfma_f32_32x32x16_bf16 v[64:79], v[228:231], v[112:115], v[64:79]
	v_add_u32_e32 v158, s14, v163
	ds_read_b128 v[220:223], v158 offset:49152
	ds_read_b128 v[228:231], v158 offset:57344
	s_waitcnt lgkmcnt(2)
	v_mfma_f32_32x32x16_bf16 v[80:95], v[236:239], v[108:111], v[80:95]
	v_mfma_f32_32x32x16_bf16 v[64:79], v[240:243], v[108:111], v[64:79]
	v_add_u32_e32 v158, s14, v164
	ds_read_b128 v[236:239], v158 offset:49152
	ds_read_b128 v[240:243], v158 offset:57344
	s_waitcnt lgkmcnt(2)
	v_mfma_f32_32x32x16_bf16 v[80:95], v[220:223], v[104:107], v[80:95]
	v_mfma_f32_32x32x16_bf16 v[64:79], v[228:231], v[104:107], v[64:79]
	v_add_u32_e32 v158, s14, v165
	ds_read_b128 v[220:223], v158 offset:49152
	ds_read_b128 v[228:231], v158 offset:57344
	s_waitcnt lgkmcnt(2)
	v_mfma_f32_32x32x16_bf16 v[80:95], v[236:239], v[100:103], v[80:95]
	v_mfma_f32_32x32x16_bf16 v[64:79], v[240:243], v[100:103], v[64:79]
	v_exp_f32_e32 v158, v146
	v_cvt_pk_bf16_f32 v146, v152, v153
	s_waitcnt lgkmcnt(0)
	v_mfma_f32_32x32x16_bf16 v[80:95], v[220:223], v[96:99], v[80:95]
	v_exp_f32_e32 v223, v128
	v_add_f32_e32 v128, 0, v206
	v_add_f32_e32 v128, v209, v128
	v_add_f32_e32 v128, v207, v128
	v_add_f32_e32 v128, v210, v128
	v_add_f32_e32 v128, v208, v128
	v_add_f32_e32 v128, v211, v128
	v_add_f32_e32 v128, v204, v128
	v_add_f32_e32 v128, v205, v128
	v_add_f32_e32 v128, v200, v128
	v_add_f32_e32 v128, v202, v128
	v_add_f32_e32 v128, v201, v128
	v_add_f32_e32 v128, v203, v128
	v_add_f32_e32 v128, v196, v128
	v_add_f32_e32 v128, v198, v128
	v_add_f32_e32 v128, v197, v128
	v_add_f32_e32 v128, v199, v128
	v_add_f32_e32 v128, v152, v128
	v_add_f32_e32 v128, v153, v128
	v_add_f32_e32 v128, v150, v128
	v_add_f32_e32 v128, v151, v128
	v_add_f32_e32 v128, v148, v128
	v_exp_f32_e32 v220, v145
	v_add_f32_e32 v128, v149, v128
	v_exp_f32_e32 v221, v130
	v_add_f32_e32 v128, v158, v128
	v_exp_f32_e32 v222, v131
	v_add_f32_e32 v128, v194, v128
	v_add_f32_e32 v128, v195, v128
	v_add_f32_e32 v128, v220, v128
	v_mfma_f32_32x32x16_bf16 v[64:79], v[228:231], v[96:99], v[64:79]
	v_exp_f32_e32 v228, v142
	v_add_f32_e32 v128, v221, v128
	v_exp_f32_e32 v229, v143
	v_add_f32_e32 v128, v222, v128
	v_add_f32_e32 v128, v223, v128
	v_add_f32_e32 v128, v227, v128
	v_add_f32_e32 v128, v228, v128
	v_add_f32_e32 v174, v229, v128
	v_mov_b32_e32 v175, v174
	v_cvt_pk_bf16_f32 v128, v206, v209
	v_cvt_pk_bf16_f32 v130, v208, v211
	s_nop 1
	v_permlane32_swap_b32_e32 v174, v175
	v_cvt_pk_bf16_f32 v131, v204, v205
	v_permlane32_swap_b32_e32 v128, v130
	v_cvt_pk_bf16_f32 v142, v200, v202
	v_cvt_pk_bf16_f32 v143, v201, v203
	v_cvt_pk_bf16_f32 v145, v197, v199
	v_cvt_pk_bf16_f32 v148, v148, v149
	v_cvt_pk_bf16_f32 v149, v158, v194
	v_cvt_pk_bf16_f32 v150, v195, v220
	v_cvt_pk_bf16_f32 v151, v221, v222
	v_cvt_pk_bf16_f32 v152, v223, v227
	v_cvt_pk_bf16_f32 v153, v228, v229
	v_permlane32_swap_b32_e32 v129, v131
	v_permlane32_swap_b32_e32 v142, v144
	v_permlane32_swap_b32_e32 v143, v145
	v_permlane32_swap_b32_e32 v146, v148
	v_permlane32_swap_b32_e32 v147, v149
	v_permlane32_swap_b32_e32 v150, v152
	v_permlane32_swap_b32_e32 v151, v153
	s_lshl_b32 s26, s44, 14
	v_add_u32_e32 v158, s26, v159
	ds_read_b64_tr_b16 v[194:195], v158 offset:0
	ds_read_b64_tr_b16 v[196:197], v158 offset:0x800
	ds_read_b64_tr_b16 v[198:199], v158 offset:0x1000
	ds_read_b64_tr_b16 v[200:201], v158 offset:0x1800
	ds_read_b64_tr_b16 v[202:203], v158 offset:0x2000
	ds_read_b64_tr_b16 v[204:205], v158 offset:0x2800
	ds_read_b64_tr_b16 v[206:207], v158 offset:0x3000
	ds_read_b64_tr_b16 v[208:209], v158 offset:0x3800
	s_waitcnt lgkmcnt(0)
	s_nop 0
	v_mfma_f32_32x32x16_bf16 v[0:15], v[128:131], v[194:197], v[0:15]
	ds_read_b64_tr_b16 v[194:195], v158 offset:0x200
	ds_read_b64_tr_b16 v[196:197], v158 offset:0xa00
	v_mfma_f32_32x32x16_bf16 v[0:15], v[142:145], v[198:201], v[0:15]
	ds_read_b64_tr_b16 v[198:199], v158 offset:0x1200
	ds_read_b64_tr_b16 v[200:201], v158 offset:0x1a00
	v_mfma_f32_32x32x16_bf16 v[0:15], v[146:149], v[202:205], v[0:15]
	ds_read_b64_tr_b16 v[202:203], v158 offset:0x2200
	ds_read_b64_tr_b16 v[204:205], v158 offset:0x2a00
	v_mfma_f32_32x32x16_bf16 v[0:15], v[150:153], v[206:209], v[0:15]
	ds_read_b64_tr_b16 v[206:207], v158 offset:0x3200
	ds_read_b64_tr_b16 v[208:209], v158 offset:0x3a00
	s_waitcnt lgkmcnt(0)
; #define SBAR() __builtin_amdgcn_sched_barrier(0)
; template <int D0> __device__ __forceinline__ void pv_one(f32x16& od, int vb, bf16x8 pa0, bf16x8 pa1, bf16x8 pa2, bf16x8 pa3) {
;     const s16x4 l0 = tr_read<v_rd_off(D0, 0, 0)>(vb), h0 = tr_read<v_rd_off(D0, 0, 1)>(vb), l1 = tr_read<v_rd_off(D0, 1, 0)>(vb), h1 = tr_read<v_rd_off(D0, 1, 1)>(vb);
;     const s16x4 l2 = tr_read<v_rd_off(D0, 2, 0)>(vb), h2 = tr_read<v_rd_off(D0, 2, 1)>(vb), l3 = tr_read<v_rd_off(D0, 3, 0)>(vb), h3 = tr_read<v_rd_off(D0, 3, 1)>(vb);
;     asm volatile("s_waitcnt lgkmcnt(0)" ::: "memory"); SBAR();
;     ...
;     od = __builtin_amdgcn_mfma_f32_32x32x16_bf16(pa0, PK(l0, h0), od, 0, 0, 0);
;     od = __builtin_amdgcn_mfma_f32_32x32x16_bf16(pa1, PK(l1, h1), od, 0, 0, 0);
;     od = __builtin_amdgcn_mfma_f32_32x32x16_bf16(pa2, PK(l2, h2), od, 0, 0, 0);
;     od = __builtin_amdgcn_mfma_f32_32x32x16_bf16(pa3, PK(l3, h3), od, 0, 0, 0);
;     ...
; }
; __device__ __forceinline__ void pv_d0(f32x16* o, int vb, bf16x8 pa0, bf16x8 pa1, bf16x8 pa2, bf16x8 pa3) {
;     pv_one<0>(o[0], vb, pa0, pa1, pa2, pa3); pv_one<1>(o[1], vb, pa0, pa1, pa2, pa3); pv_one<2>(o[2], vb, pa0, pa1, pa2, pa3); pv_one<3>(o[3], vb, pa0, pa1, pa2, pa3);
; }
; __device__ __forceinline__ void partialSM(f32x16& p0, f32x16& p1, float& m_reg, float& mn, float& alpha, const float C, const float thr_raw) {
;     float pmax = p0[0];
; #pragma unroll
;     for (int r = 1; r < 16; ++r) pmax = fmaxf(pmax, p0[r]);
; #pragma unroll
;     for (int r = 0; r < 16; ++r) pmax = fmaxf(pmax, p1[r]);
;     { auto rr = __builtin_amdgcn_permlane32_swap(__float_as_uint(pmax), __float_as_uint(pmax), false, false);
;       pmax = fmaxf(__uint_as_float(rr[0]), __uint_as_float(rr[1])); }
;     if (__builtin_expect(__all(pmax - m_reg <= thr_raw), 1)) { mn = m_reg; alpha = 1.f; }
;     else { mn = fmaxf(m_reg, pmax); alpha = __builtin_amdgcn_exp2f((m_reg - mn) * C); m_reg = mn; }
	v_mfma_f32_32x32x16_bf16 v[48:63], v[128:131], v[194:197], v[48:63]
	ds_read_b64_tr_b16 v[194:195], v158 offset:0x400
	ds_read_b64_tr_b16 v[196:197], v158 offset:0xc00
	v_mfma_f32_32x32x16_bf16 v[48:63], v[142:145], v[198:201], v[48:63]
	ds_read_b64_tr_b16 v[198:199], v158 offset:0x1400
	ds_read_b64_tr_b16 v[200:201], v158 offset:0x1c00
	v_mfma_f32_32x32x16_bf16 v[48:63], v[146:149], v[202:205], v[48:63]
	ds_read_b64_tr_b16 v[202:203], v158 offset:0x2400
	ds_read_b64_tr_b16 v[204:205], v158 offset:0x2c00
	v_mfma_f32_32x32x16_bf16 v[48:63], v[150:153], v[206:209], v[48:63]
	ds_read_b64_tr_b16 v[206:207], v158 offset:0x3400
	ds_read_b64_tr_b16 v[208:209], v158 offset:0x3c00
	s_waitcnt lgkmcnt(0)
	v_mfma_f32_32x32x16_bf16 v[32:47], v[128:131], v[194:197], v[32:47]
	ds_read_b64_tr_b16 v[194:195], v158 offset:0x600
	ds_read_b64_tr_b16 v[196:197], v158 offset:0xe00
	v_mfma_f32_32x32x16_bf16 v[32:47], v[142:145], v[198:201], v[32:47]
	ds_read_b64_tr_b16 v[198:199], v158 offset:0x1600
	ds_read_b64_tr_b16 v[200:201], v158 offset:0x1e00
	v_mfma_f32_32x32x16_bf16 v[32:47], v[146:149], v[202:205], v[32:47]
	ds_read_b64_tr_b16 v[202:203], v158 offset:0x2600
	ds_read_b64_tr_b16 v[204:205], v158 offset:0x2e00
	v_mfma_f32_32x32x16_bf16 v[32:47], v[150:153], v[206:209], v[32:47]
	ds_read_b64_tr_b16 v[206:207], v158 offset:0x3600
	ds_read_b64_tr_b16 v[208:209], v158 offset:0x3e00
	s_waitcnt lgkmcnt(0)
	v_mfma_f32_32x32x16_bf16 v[16:31], v[128:131], v[194:197], v[16:31]
	v_max_f32_e32 v128, v81, v81
	v_max_f32_e32 v129, v80, v80
	v_max_f32_e32 v128, v129, v128
	v_max3_f32 v128, v128, v82, v83
	v_max3_f32 v128, v128, v84, v85
	v_max3_f32 v128, v128, v86, v87
	v_max3_f32 v128, v128, v88, v89
	v_mfma_f32_32x32x16_bf16 v[16:31], v[142:145], v[198:201], v[16:31]
	v_max3_f32 v128, v128, v90, v91
	v_max3_f32 v128, v128, v92, v93
	v_max3_f32 v128, v128, v94, v95
	v_max3_f32 v128, v128, v64, v65
	v_max3_f32 v128, v128, v66, v67
	v_max3_f32 v128, v128, v68, v69
	v_max3_f32 v128, v128, v70, v71
	v_mfma_f32_32x32x16_bf16 v[16:31], v[146:149], v[202:205], v[16:31]
	v_max3_f32 v128, v128, v72, v73
	v_max3_f32 v128, v128, v74, v75
	v_max3_f32 v128, v128, v76, v77
	v_max3_f32 v128, v128, v78, v79
	v_mov_b32_e32 v129, v128
	s_nop 1
	v_permlane32_swap_b32_e32 v128, v129
	v_mfma_f32_32x32x16_bf16 v[16:31], v[150:153], v[206:209], v[16:31]
	v_max_f32_e32 v129, v129, v129
	v_max_f32_e32 v128, v128, v128
	v_max_f32_e32 v128, v128, v129
	v_sub_f32_e32 v129, v128, v172
	v_cmp_ge_f32_e32 vcc, s20, v129
	s_cmp_eq_u64 vcc, exec
	s_waitcnt vmcnt(0)
	s_cselect_b64 s[40:41], -1, 0
	s_add_i32 s14, s22, -1
	v_cmp_lt_u32_e32 vcc, s14, v160
	s_waitcnt vmcnt(0)
	s_barrier
	s_mov_b32 s100, vcc_lo
.LBB0_3451:
	v_max_f32_e32 v129, v172, v172
	v_max_f32_e32 v128, v129, v128
	v_sub_f32_e32 v129, v172, v128
	v_mul_f32_e32 v129, 0x3e0293ee, v129
	v_exp_f32_e32 v129, v129
	s_nop 0
	v_cndmask_b32_e64 v195, v129, 1.0, s[40:41]
	v_cmp_gt_f32_e32 vcc, 1.0, v195
	s_cbranch_vccz .LBB0_3455
	s_and_saveexec_b64 s[42:43], s[38:39]
	ds_write_b32 v157, v195 offset:128
	s_or_b64 exec, exec, s[42:43]
	s_waitcnt lgkmcnt(0)
	v_add_u32_e32 v129, s1, v178
	ds_read_b128 v[142:145], v129 offset:224
	ds_read_b128 v[146:149], v129 offset:192
	ds_read_b128 v[150:153], v129 offset:160
	ds_read_b128 v[196:199], v129 offset:128
	s_waitcnt lgkmcnt(0)
	v_pk_mul_f32 v[12:13], v[12:13], v[142:143]
	v_pk_mul_f32 v[8:9], v[8:9], v[146:147]
	v_pk_mul_f32 v[4:5], v[4:5], v[150:151]
	v_pk_mul_f32 v[14:15], v[14:15], v[144:145]
	v_pk_mul_f32 v[10:11], v[10:11], v[148:149]
	v_pk_mul_f32 v[6:7], v[6:7], v[152:153]
	v_pk_mul_f32 v[2:3], v[2:3], v[198:199]
	v_pk_mul_f32 v[0:1], v[0:1], v[196:197]
	v_pk_mul_f32 v[60:61], v[60:61], v[142:143]
	v_pk_mul_f32 v[56:57], v[56:57], v[146:147]
	v_pk_mul_f32 v[52:53], v[52:53], v[150:151]
	v_pk_mul_f32 v[62:63], v[62:63], v[144:145]
	v_pk_mul_f32 v[58:59], v[58:59], v[148:149]
	v_pk_mul_f32 v[54:55], v[54:55], v[152:153]
	v_pk_mul_f32 v[50:51], v[50:51], v[198:199]
	v_pk_mul_f32 v[48:49], v[48:49], v[196:197]
	v_pk_mul_f32 v[44:45], v[44:45], v[142:143]
	v_pk_mul_f32 v[40:41], v[40:41], v[146:147]
	v_pk_mul_f32 v[36:37], v[36:37], v[150:151]
	v_pk_mul_f32 v[46:47], v[46:47], v[144:145]
	v_pk_mul_f32 v[42:43], v[42:43], v[148:149]
	v_pk_mul_f32 v[38:39], v[38:39], v[152:153]
	v_pk_mul_f32 v[34:35], v[34:35], v[198:199]
	v_pk_mul_f32 v[32:33], v[32:33], v[196:197]
	v_pk_mul_f32 v[28:29], v[28:29], v[142:143]
	v_pk_mul_f32 v[24:25], v[24:25], v[146:147]
	v_pk_mul_f32 v[20:21], v[20:21], v[150:151]
	v_pk_mul_f32 v[30:31], v[30:31], v[144:145]
	v_pk_mul_f32 v[26:27], v[26:27], v[148:149]
	v_pk_mul_f32 v[22:23], v[22:23], v[152:153]
	v_pk_mul_f32 v[18:19], v[18:19], v[198:199]
	v_pk_mul_f32 v[16:17], v[16:17], v[196:197]
; __device__ __forceinline__ void partialSM(f32x16& p0, f32x16& p1, float& m_reg, float& mn, float& alpha, const float C, const float thr_raw) {
;     ...
;     const float mnC = -mn * C;
; #pragma unroll
;     for (int r = 0; r < 16; ++r) p0[r] = fmaf(p0[r], C, mnC);
; #pragma unroll
;     for (int r = 0; r < 16; ++r) p1[r] = fmaf(p1[r], C, mnC);
; #pragma unroll
;     for (int r = 0; r < 16; ++r) p0[r] = __builtin_amdgcn_exp2f(p0[r]);
; }
; __device__ __forceinline__ void finishSM(f32x16& p0, f32x16& p1, float alpha, float& l_reg, bf16x8& pa0, bf16x8& pa1, bf16x8& pa2, bf16x8& pa3) {
; #pragma unroll
;     for (int r = 0; r < 16; ++r) p1[r] = __builtin_amdgcn_exp2f(p1[r]);
;     float ps = 0;
; #pragma unroll
;     for (int r = 0; r < 16; ++r) ps += p0[r];
; #pragma unroll
;     for (int r = 0; r < 16; ++r) ps += p1[r];
;     { auto rr = __builtin_amdgcn_permlane32_swap(__float_as_uint(ps), __float_as_uint(ps), false, false);
;       ps = __uint_as_float(rr[0]) + __uint_as_float(rr[1]); }
;     l_reg = l_reg * alpha + ps;
;     ...
;     PK4(p0, 0, pa0); PK4(p0, 8, pa1); PK4(p1, 0, pa2); PK4(p1, 8, pa3);
;     ...
; }
; template <int DQK> __device__ __forceinline__ void qkt(f32x16& p0, f32x16& p1, const char* Ks, const bf16x8* qr, int r32, int hi) {
;     p0 = f32x16{}; p1 = f32x16{};
; #pragma unroll
;     for (int d0 = 0; d0 < DQK / 16; ++d0) { const int cb = (d0 * 16 + hi * 8) * 2;
;         const bf16x8 b0 = *reinterpret_cast<const bf16x8*>(Ks + kswz<DQK>(r32, cb));
;         const bf16x8 b1 = *reinterpret_cast<const bf16x8*>(Ks + kswz<DQK>(32 + r32, cb));
;         p0 = __builtin_amdgcn_mfma_f32_32x32x16_bf16(b0, qr[d0], p0, 0, 0, 0);
;         p1 = __builtin_amdgcn_mfma_f32_32x32x16_bf16(b1, qr[d0], p1, 0, 0, 0); }
; }
.LBB0_3455:
	v_cndmask_b32_e64 v142, v128, v172, s[40:41]
	v_mul_f32_e32 v194, 0xbe0293ee, v142
	v_fmamk_f32 v80, v80, 0x3e0293ee, v194
	v_exp_f32_e32 v128, v80
	v_fmamk_f32 v81, v81, 0x3e0293ee, v194
	v_fmamk_f32 v82, v82, 0x3e0293ee, v194
	v_fmamk_f32 v83, v83, 0x3e0293ee, v194
	v_fmamk_f32 v84, v84, 0x3e0293ee, v194
	v_fmamk_f32 v85, v85, 0x3e0293ee, v194
	v_fmamk_f32 v86, v86, 0x3e0293ee, v194
	v_fmamk_f32 v87, v87, 0x3e0293ee, v194
	v_fmamk_f32 v88, v88, 0x3e0293ee, v194
	v_fmamk_f32 v89, v89, 0x3e0293ee, v194
	v_fmamk_f32 v90, v90, 0x3e0293ee, v194
	v_fmamk_f32 v91, v91, 0x3e0293ee, v194
	v_fmamk_f32 v92, v92, 0x3e0293ee, v194
	v_fmamk_f32 v93, v93, 0x3e0293ee, v194
	v_fmamk_f32 v94, v94, 0x3e0293ee, v194
	v_fmamk_f32 v95, v95, 0x3e0293ee, v194
	v_fmamk_f32 v204, v64, 0x3e0293ee, v194
	v_fmamk_f32 v205, v65, 0x3e0293ee, v194
	v_fmamk_f32 v206, v66, 0x3e0293ee, v194
	v_fmamk_f32 v207, v67, 0x3e0293ee, v194
	v_fmamk_f32 v208, v68, 0x3e0293ee, v194
	v_fmamk_f32 v197, v69, 0x3e0293ee, v194
	v_fmamk_f32 v198, v70, 0x3e0293ee, v194
	v_fmamk_f32 v199, v71, 0x3e0293ee, v194
	v_fmamk_f32 v200, v72, 0x3e0293ee, v194
	v_fmamk_f32 v201, v73, 0x3e0293ee, v194
	v_fmamk_f32 v202, v74, 0x3e0293ee, v194
	v_fmamk_f32 v203, v75, 0x3e0293ee, v194
	v_fmamk_f32 v196, v76, 0x3e0293ee, v194
	v_exp_f32_e32 v172, v81
	v_exp_f32_e32 v129, v82
	v_exp_f32_e32 v153, v83
	v_exp_f32_e32 v130, v84
	v_exp_f32_e32 v152, v85
	v_exp_f32_e32 v131, v86
	v_exp_f32_e32 v151, v87
	v_exp_f32_e32 v148, v88
	v_exp_f32_e32 v150, v89
	v_exp_f32_e32 v147, v90
	v_exp_f32_e32 v149, v91
	v_exp_f32_e32 v144, v92
	v_exp_f32_e32 v146, v93
	v_exp_f32_e32 v143, v94
	v_exp_f32_e32 v145, v95
	v_fmamk_f32 v209, v77, 0x3e0293ee, v194
	v_fmamk_f32 v210, v78, 0x3e0293ee, v194
	v_fmac_f32_e32 v194, 0x3e0293ee, v79
	s_lshl_b32 s27, s24, 14
	s_add_i32 s14, s27, 0
	v_add_u32_e32 v68, s14, v169
	ds_read_b128 v[64:67], v68 offset:49152
	ds_read_b128 v[68:71], v68 offset:57344
	v_add_u32_e32 v211, s14, v171
	ds_read_b128 v[220:223], v211 offset:49152
	ds_read_b128 v[228:231], v211 offset:57344
	v_add_u32_e32 v211, s14, v170
	ds_read_b128 v[236:239], v211 offset:49152
	ds_read_b128 v[240:243], v211 offset:57344
	s_waitcnt lgkmcnt(4)
	v_mfma_f32_32x32x16_bf16 v[80:95], v[64:67], v[124:127], 0
	v_exp_f32_e32 v204, v204
	v_exp_f32_e32 v205, v205
	v_exp_f32_e32 v206, v206
	v_exp_f32_e32 v207, v207
	v_exp_f32_e32 v208, v208
	v_exp_f32_e32 v197, v197
	v_exp_f32_e32 v198, v198
	v_mfma_f32_32x32x16_bf16 v[64:79], v[68:71], v[124:127], 0
	v_exp_f32_e32 v199, v199
	v_exp_f32_e32 v200, v200
	v_exp_f32_e32 v201, v201
	v_exp_f32_e32 v202, v202
	v_exp_f32_e32 v203, v203
	v_exp_f32_e32 v209, v209
	v_exp_f32_e32 v210, v210
	s_waitcnt lgkmcnt(2)
	v_mfma_f32_32x32x16_bf16 v[80:95], v[220:223], v[120:123], v[80:95]
	v_exp_f32_e32 v194, v194
	v_mfma_f32_32x32x16_bf16 v[64:79], v[228:231], v[120:123], v[64:79]
	v_add_u32_e32 v211, s14, v168
	ds_read_b128 v[220:223], v211 offset:49152
	ds_read_b128 v[228:231], v211 offset:57344
	s_waitcnt lgkmcnt(2)
	v_mfma_f32_32x32x16_bf16 v[80:95], v[236:239], v[116:119], v[80:95]
	v_mfma_f32_32x32x16_bf16 v[64:79], v[240:243], v[116:119], v[64:79]
	s_cmp_eq_u32 s100, 0
	s_cbranch_scc1 .Lstage_skip_0
	s_sub_i32 s101, s23, 64
	v_cmp_lt_u32_e32 vcc, s101, v161
	s_nop 1
	v_cndmask_b32_e32 v232, v166, v162, vcc
	v_add_u32_e32 v244, s101, v232
	v_ashrrev_i32_e32 v245, 31, v244
	v_lshlrev_b64 v[244:245], 8, v[244:245]
	v_lshl_add_u64 v[246:247], s[86:87], 0, v[244:245]
	s_add_i32 s101, s6, s26
	v_lshl_add_u64 v[248:249], v[134:135], 1, v[246:247]
	s_mov_b32 m0, s101
	v_lshl_add_u64 v[246:247], v[136:137], 1, v[246:247]
	global_load_lds_dwordx4 v[248:249], off
	s_add_i32 m0, s101, 0x2000
	v_lshl_add_u64 v[244:245], s[84:85], 0, v[244:245]
	global_load_lds_dwordx4 v[246:247], off
	s_add_i32 m0, s101, 0xc000
	v_lshl_add_u64 v[246:247], v[138:139], 1, v[244:245]
	global_load_lds_dwordx4 v[246:247], off
	v_lshl_add_u64 v[244:245], v[140:141], 1, v[244:245]
	s_add_i32 m0, s101, 0xe000
	s_nop 0
	global_load_lds_dwordx4 v[244:245], off
.Lstage_skip_0:
	v_add_u32_e32 v211, s14, v167
	ds_read_b128 v[236:239], v211 offset:49152
	ds_read_b128 v[240:243], v211 offset:57344
	s_waitcnt lgkmcnt(2)
	v_mfma_f32_32x32x16_bf16 v[80:95], v[220:223], v[112:115], v[80:95]
	v_mfma_f32_32x32x16_bf16 v[64:79], v[228:231], v[112:115], v[64:79]
	v_add_u32_e32 v211, s14, v163
	ds_read_b128 v[220:223], v211 offset:49152
	ds_read_b128 v[228:231], v211 offset:57344
	s_waitcnt lgkmcnt(2)
	v_mfma_f32_32x32x16_bf16 v[80:95], v[236:239], v[108:111], v[80:95]
	v_mfma_f32_32x32x16_bf16 v[64:79], v[240:243], v[108:111], v[64:79]
	v_add_u32_e32 v211, s14, v164
	ds_read_b128 v[236:239], v211 offset:49152
	ds_read_b128 v[240:243], v211 offset:57344
	s_waitcnt lgkmcnt(2)
	v_mfma_f32_32x32x16_bf16 v[80:95], v[220:223], v[104:107], v[80:95]
	v_mfma_f32_32x32x16_bf16 v[64:79], v[228:231], v[104:107], v[64:79]
	v_add_u32_e32 v211, s14, v165
	ds_read_b128 v[220:223], v211 offset:49152
	ds_read_b128 v[228:231], v211 offset:57344
	s_waitcnt lgkmcnt(2)
	v_mfma_f32_32x32x16_bf16 v[80:95], v[236:239], v[100:103], v[80:95]
	v_mfma_f32_32x32x16_bf16 v[64:79], v[240:243], v[100:103], v[64:79]
	v_exp_f32_e32 v211, v196
	v_add_f32_e32 v196, 0, v128
	v_add_f32_e32 v196, v172, v196
	v_add_f32_e32 v196, v129, v196
	v_add_f32_e32 v196, v153, v196
	v_add_f32_e32 v196, v130, v196
	v_add_f32_e32 v196, v152, v196
	v_add_f32_e32 v196, v131, v196
	v_add_f32_e32 v196, v151, v196
	v_add_f32_e32 v196, v148, v196
	v_add_f32_e32 v196, v150, v196
	v_add_f32_e32 v196, v147, v196
	v_add_f32_e32 v196, v149, v196
	v_add_f32_e32 v196, v144, v196
	v_add_f32_e32 v196, v146, v196
	v_add_f32_e32 v196, v143, v196
	v_add_f32_e32 v196, v145, v196
	v_add_f32_e32 v196, v204, v196
	v_add_f32_e32 v196, v205, v196
	v_add_f32_e32 v196, v206, v196
	v_add_f32_e32 v196, v207, v196
	v_add_f32_e32 v196, v208, v196
	v_add_f32_e32 v196, v197, v196
	v_add_f32_e32 v196, v198, v196
	v_add_f32_e32 v196, v199, v196
	v_add_f32_e32 v196, v200, v196
	v_add_f32_e32 v196, v201, v196
	s_waitcnt lgkmcnt(0)
; template <int D0> __device__ __forceinline__ void pv_one(f32x16& od, int vb, bf16x8 pa0, bf16x8 pa1, bf16x8 pa2, bf16x8 pa3) {
;     const s16x4 l0 = tr_read<v_rd_off(D0, 0, 0)>(vb), h0 = tr_read<v_rd_off(D0, 0, 1)>(vb), l1 = tr_read<v_rd_off(D0, 1, 0)>(vb), h1 = tr_read<v_rd_off(D0, 1, 1)>(vb);
;     const s16x4 l2 = tr_read<v_rd_off(D0, 2, 0)>(vb), h2 = tr_read<v_rd_off(D0, 2, 1)>(vb), l3 = tr_read<v_rd_off(D0, 3, 0)>(vb), h3 = tr_read<v_rd_off(D0, 3, 1)>(vb);
;     asm volatile("s_waitcnt lgkmcnt(0)" ::: "memory"); SBAR();
;     ...
;     od = __builtin_amdgcn_mfma_f32_32x32x16_bf16(pa0, PK(l0, h0), od, 0, 0, 0);
;     od = __builtin_amdgcn_mfma_f32_32x32x16_bf16(pa1, PK(l1, h1), od, 0, 0, 0);
;     od = __builtin_amdgcn_mfma_f32_32x32x16_bf16(pa2, PK(l2, h2), od, 0, 0, 0);
;     od = __builtin_amdgcn_mfma_f32_32x32x16_bf16(pa3, PK(l3, h3), od, 0, 0, 0);
;     ...
; }
; __device__ __forceinline__ void pv_d0(f32x16* o, int vb, bf16x8 pa0, bf16x8 pa1, bf16x8 pa2, bf16x8 pa3) {
;     pv_one<0>(o[0], vb, pa0, pa1, pa2, pa3); pv_one<1>(o[1], vb, pa0, pa1, pa2, pa3); pv_one<2>(o[2], vb, pa0, pa1, pa2, pa3); pv_one<3>(o[3], vb, pa0, pa1, pa2, pa3);
; }
; __device__ __forceinline__ void partialSM(f32x16& p0, f32x16& p1, float& m_reg, float& mn, float& alpha, const float C, const float thr_raw) {
;     float pmax = p0[0];
; #pragma unroll
;     for (int r = 1; r < 16; ++r) pmax = fmaxf(pmax, p0[r]);
; #pragma unroll
;     for (int r = 0; r < 16; ++r) pmax = fmaxf(pmax, p1[r]);
;     { auto rr = __builtin_amdgcn_permlane32_swap(__float_as_uint(pmax), __float_as_uint(pmax), false, false);
;       pmax = fmaxf(__uint_as_float(rr[0]), __uint_as_float(rr[1])); }
;     if (__builtin_expect(__all(pmax - m_reg <= thr_raw), 1)) { mn = m_reg; alpha = 1.f; }
;     else { mn = fmaxf(m_reg, pmax); alpha = __builtin_amdgcn_exp2f((m_reg - mn) * C); m_reg = mn; }
;     const float mnC = -mn * C;
; #pragma unroll
;     for (int r = 0; r < 16; ++r) p0[r] = fmaf(p0[r], C, mnC);
; #pragma unroll
;     for (int r = 0; r < 16; ++r) p1[r] = fmaf(p1[r], C, mnC);
; #pragma unroll
;     for (int r = 0; r < 16; ++r) p0[r] = __builtin_amdgcn_exp2f(p0[r]);
; }
; __device__ __forceinline__ void finishSM(f32x16& p0, f32x16& p1, float alpha, float& l_reg, bf16x8& pa0, bf16x8& pa1, bf16x8& pa2, bf16x8& pa3) {
; #pragma unroll
;     for (int r = 0; r < 16; ++r) p1[r] = __builtin_amdgcn_exp2f(p1[r]);
	v_mfma_f32_32x32x16_bf16 v[80:95], v[220:223], v[96:99], v[80:95]
	v_add_f32_e32 v196, v202, v196
	v_add_f32_e32 v196, v203, v196
	v_add_f32_e32 v196, v211, v196
	v_add_f32_e32 v196, v209, v196
	v_add_f32_e32 v196, v210, v196
	v_add_f32_e32 v227, v194, v196
	v_cvt_pk_bf16_f32 v128, v128, v172
	v_mfma_f32_32x32x16_bf16 v[64:79], v[228:231], v[96:99], v[64:79]
	v_mov_b32_e32 v228, v227
	v_cvt_pk_bf16_f32 v130, v130, v152
	s_nop 1
	v_permlane32_swap_b32_e32 v227, v228
	v_cvt_pk_bf16_f32 v129, v129, v153
	v_cvt_pk_bf16_f32 v131, v131, v151
	v_permlane32_swap_b32_e32 v128, v130
	v_cvt_pk_bf16_f32 v148, v148, v150
	v_cvt_pk_bf16_f32 v149, v147, v149
	v_cvt_pk_bf16_f32 v150, v144, v146
	v_cvt_pk_bf16_f32 v151, v143, v145
	v_cvt_pk_bf16_f32 v144, v204, v205
	v_cvt_pk_bf16_f32 v145, v206, v207
	v_cvt_pk_bf16_f32 v146, v208, v197
	v_cvt_pk_bf16_f32 v147, v198, v199
	v_cvt_pk_bf16_f32 v196, v200, v201
	v_cvt_pk_bf16_f32 v197, v202, v203
	v_cvt_pk_bf16_f32 v198, v211, v209
	v_cvt_pk_bf16_f32 v199, v210, v194
	v_permlane32_swap_b32_e32 v129, v131
	v_permlane32_swap_b32_e32 v148, v150
	v_permlane32_swap_b32_e32 v149, v151
	v_permlane32_swap_b32_e32 v144, v146
	v_permlane32_swap_b32_e32 v145, v147
	v_permlane32_swap_b32_e32 v196, v198
	v_permlane32_swap_b32_e32 v197, v199
	v_add_u32_e32 v143, s25, v159
	ds_read_b64_tr_b16 v[200:201], v143 offset:0
	ds_read_b64_tr_b16 v[202:203], v143 offset:0x800
	ds_read_b64_tr_b16 v[204:205], v143 offset:0x1000
	ds_read_b64_tr_b16 v[206:207], v143 offset:0x1800
	ds_read_b64_tr_b16 v[208:209], v143 offset:0x2000
	ds_read_b64_tr_b16 v[210:211], v143 offset:0x2800
	ds_read_b64_tr_b16 v[220:221], v143 offset:0x3000
	ds_read_b64_tr_b16 v[222:223], v143 offset:0x3800
	s_waitcnt lgkmcnt(0)
	s_nop 0
	v_mfma_f32_32x32x16_bf16 v[0:15], v[128:131], v[200:203], v[0:15]
	ds_read_b64_tr_b16 v[200:201], v143 offset:0x200
	ds_read_b64_tr_b16 v[202:203], v143 offset:0xa00
	v_mfma_f32_32x32x16_bf16 v[0:15], v[148:151], v[204:207], v[0:15]
	ds_read_b64_tr_b16 v[204:205], v143 offset:0x1200
	ds_read_b64_tr_b16 v[206:207], v143 offset:0x1a00
	v_mfma_f32_32x32x16_bf16 v[0:15], v[144:147], v[208:211], v[0:15]
	ds_read_b64_tr_b16 v[208:209], v143 offset:0x2200
	ds_read_b64_tr_b16 v[210:211], v143 offset:0x2a00
	v_mfma_f32_32x32x16_bf16 v[0:15], v[196:199], v[220:223], v[0:15]
	ds_read_b64_tr_b16 v[220:221], v143 offset:0x3200
	ds_read_b64_tr_b16 v[222:223], v143 offset:0x3a00
	s_waitcnt lgkmcnt(0)
	v_mfma_f32_32x32x16_bf16 v[48:63], v[128:131], v[200:203], v[48:63]
	ds_read_b64_tr_b16 v[200:201], v143 offset:0x400
	ds_read_b64_tr_b16 v[202:203], v143 offset:0xc00
	v_mfma_f32_32x32x16_bf16 v[48:63], v[148:151], v[204:207], v[48:63]
	ds_read_b64_tr_b16 v[204:205], v143 offset:0x1400
	ds_read_b64_tr_b16 v[206:207], v143 offset:0x1c00
	v_mfma_f32_32x32x16_bf16 v[48:63], v[144:147], v[208:211], v[48:63]
	ds_read_b64_tr_b16 v[208:209], v143 offset:0x2400
	ds_read_b64_tr_b16 v[210:211], v143 offset:0x2c00
	v_mfma_f32_32x32x16_bf16 v[48:63], v[196:199], v[220:223], v[48:63]
	ds_read_b64_tr_b16 v[220:221], v143 offset:0x3400
	ds_read_b64_tr_b16 v[222:223], v143 offset:0x3c00
	s_waitcnt lgkmcnt(0)
	v_mfma_f32_32x32x16_bf16 v[32:47], v[128:131], v[200:203], v[32:47]
	ds_read_b64_tr_b16 v[200:201], v143 offset:0x600
	ds_read_b64_tr_b16 v[202:203], v143 offset:0xe00
	v_mfma_f32_32x32x16_bf16 v[32:47], v[148:151], v[204:207], v[32:47]
	ds_read_b64_tr_b16 v[204:205], v143 offset:0x1600
	ds_read_b64_tr_b16 v[206:207], v143 offset:0x1e00
	v_mfma_f32_32x32x16_bf16 v[32:47], v[144:147], v[208:211], v[32:47]
	ds_read_b64_tr_b16 v[208:209], v143 offset:0x2600
	ds_read_b64_tr_b16 v[210:211], v143 offset:0x2e00
	v_mfma_f32_32x32x16_bf16 v[32:47], v[196:199], v[220:223], v[32:47]
	ds_read_b64_tr_b16 v[220:221], v143 offset:0x3600
	ds_read_b64_tr_b16 v[222:223], v143 offset:0x3e00
	s_waitcnt lgkmcnt(0)
	v_mfma_f32_32x32x16_bf16 v[16:31], v[128:131], v[200:203], v[16:31]
	v_max_f32_e32 v128, v81, v81
	v_max_f32_e32 v129, v80, v80
	v_max_f32_e32 v128, v129, v128
	v_max3_f32 v128, v128, v82, v83
	v_max3_f32 v128, v128, v84, v85
	v_max3_f32 v128, v128, v86, v87
	v_max3_f32 v128, v128, v88, v89
	v_mfma_f32_32x32x16_bf16 v[16:31], v[148:151], v[204:207], v[16:31]
	v_max3_f32 v128, v128, v90, v91
	v_max3_f32 v128, v128, v92, v93
	v_max3_f32 v128, v128, v94, v95
	v_max3_f32 v128, v128, v64, v65
	v_max3_f32 v128, v128, v66, v67
	v_max3_f32 v128, v128, v68, v69
	v_max3_f32 v128, v128, v70, v71
	v_mfma_f32_32x32x16_bf16 v[16:31], v[144:147], v[208:211], v[16:31]
	v_max3_f32 v128, v128, v72, v73
	v_max3_f32 v128, v128, v74, v75
	v_max3_f32 v128, v128, v76, v77
	v_max3_f32 v128, v128, v78, v79
	v_mov_b32_e32 v129, v128
	s_nop 1
	v_permlane32_swap_b32_e32 v128, v129
	v_mfma_f32_32x32x16_bf16 v[16:31], v[196:199], v[220:223], v[16:31]
	v_max_f32_e32 v129, v129, v129
	v_max_f32_e32 v128, v128, v128
	v_max_f32_e32 v128, v128, v129
	v_sub_f32_e32 v129, v128, v142
	v_cmp_ge_f32_e32 vcc, s20, v129
	s_waitcnt vmcnt(0)
	s_cmp_eq_u64 vcc, exec
	s_cselect_b64 s[42:43], -1, 0
	v_cmp_lt_u32_e32 vcc, s22, v160
	v_cmp_ge_u32_e64 s[40:41], s22, v160
	s_waitcnt vmcnt(0)
	s_barrier
	s_and_saveexec_b64 s[48:49], vcc
	s_cbranch_execz .LBB0_3457
	v_cmp_lt_u32_e32 vcc, s23, v161
	s_add_i32 s14, s6, s25
	s_mov_b32 m0, s14
	v_cndmask_b32_e32 v129, v166, v162, vcc
	v_add_u32_e32 v130, s23, v129
	v_ashrrev_i32_e32 v131, 31, v130
	v_lshlrev_b64 v[130:131], 8, v[130:131]
	v_lshl_add_u64 v[144:145], s[86:87], 0, v[130:131]
	v_lshl_add_u64 v[146:147], v[134:135], 1, v[144:145]
	global_load_lds_dwordx4 v[146:147], off
	v_lshl_add_u64 v[144:145], v[136:137], 1, v[144:145]
	s_add_i32 m0, s14, 0x2000
	v_lshl_add_u64 v[130:131], s[84:85], 0, v[130:131]
	global_load_lds_dwordx4 v[144:145], off
	s_add_i32 m0, s14, 0xc000
	v_lshl_add_u64 v[144:145], v[138:139], 1, v[130:131]
	global_load_lds_dwordx4 v[144:145], off
	v_lshl_add_u64 v[130:131], v[140:141], 1, v[130:131]
	s_add_i32 m0, s14, 0xe000
	s_nop 0
	global_load_lds_dwordx4 v[130:131], off

; #define LAS __attribute__((address_space(3)))
; __global__ void __launch_bounds__(512) fwd_megakernel(Params p) {
;     extern __shared__ __attribute__((aligned(16))) unsigned char smem[];
;     char* lds = (char*)smem;
;     LAS unsigned char* ldsl = (LAS unsigned char*)smem;
;     cg::grid_group grid = cg::this_grid();
;     unsigned char* ws = p.ws;
;     const int tid = threadIdx.x, G = gridDim.x, bid = blockIdx.x;
	.amdhsa_kernel _Z14fwd_megakernel6Params
		.amdhsa_group_segment_fixed_size 0
		.amdhsa_private_segment_fixed_size 0
		.amdhsa_kernarg_size 448
		.amdhsa_user_sgpr_count 2
		.amdhsa_user_sgpr_dispatch_ptr 0
		.amdhsa_user_sgpr_queue_ptr 0
		.amdhsa_user_sgpr_kernarg_segment_ptr 1
		.amdhsa_user_sgpr_dispatch_id 0
		.amdhsa_user_sgpr_kernarg_preload_length 0
		.amdhsa_user_sgpr_kernarg_preload_offset 0
		.amdhsa_user_sgpr_private_segment_size 0
		.amdhsa_uses_dynamic_stack 0
		.amdhsa_enable_private_segment 0
		.amdhsa_system_sgpr_workgroup_id_x 1
		.amdhsa_system_sgpr_workgroup_id_y 0
		.amdhsa_system_sgpr_workgroup_id_z 0
		.amdhsa_system_sgpr_workgroup_info 0
		.amdhsa_system_vgpr_workitem_id 2
		.amdhsa_next_free_vgpr 256
		.amdhsa_next_free_sgpr 102
		.amdhsa_accum_offset 256
		.amdhsa_reserve_vcc 1
		.amdhsa_float_round_mode_32 0
		.amdhsa_float_round_mode_16_64 0
		.amdhsa_float_denorm_mode_32 3
		.amdhsa_float_denorm_mode_16_64 3
		.amdhsa_dx10_clamp 1
		.amdhsa_ieee_mode 1
		.amdhsa_fp16_overflow 0
		.amdhsa_tg_split 0
		.amdhsa_exception_fp_ieee_invalid_op 0
		.amdhsa_exception_fp_denorm_src 0
		.amdhsa_exception_fp_ieee_div_zero 0
		.amdhsa_exception_fp_ieee_overflow 0
		.amdhsa_exception_fp_ieee_underflow 0
		.amdhsa_exception_fp_ieee_inexact 0
		.amdhsa_exception_int_div_zero 0
	.end_amdhsa_kernel

; #define LAS __attribute__((address_space(3)))
; __global__ void __launch_bounds__(512) fwd_megakernel(Params p) {
;     extern __shared__ __attribute__((aligned(16))) unsigned char smem[];
;     char* lds = (char*)smem;
;     LAS unsigned char* ldsl = (LAS unsigned char*)smem;
;     cg::grid_group grid = cg::this_grid();
;     unsigned char* ws = p.ws;
;     const int tid = threadIdx.x, G = gridDim.x, bid = blockIdx.x;
amdhsa.kernels:
  - .agpr_count:     0
    .args:
      - .offset:         0
        .size:           192
        .value_kind:     by_value
      - .offset:         192
        .size:           4
        .value_kind:     hidden_block_count_x
      - .offset:         196
        .size:           4
        .value_kind:     hidden_block_count_y
      - .offset:         200
        .size:           4
        .value_kind:     hidden_block_count_z
      - .offset:         204
        .size:           2
        .value_kind:     hidden_group_size_x
      - .offset:         206
        .size:           2
        .value_kind:     hidden_group_size_y
      - .offset:         208
        .size:           2
        .value_kind:     hidden_group_size_z
      - .offset:         210
        .size:           2
        .value_kind:     hidden_remainder_x
      - .offset:         212
        .size:           2
        .value_kind:     hidden_remainder_y
      - .offset:         214
        .size:           2
        .value_kind:     hidden_remainder_z
      - .offset:         232
        .size:           8
        .value_kind:     hidden_global_offset_x
      - .offset:         240
        .size:           8
        .value_kind:     hidden_global_offset_y
      - .offset:         248
        .size:           8
        .value_kind:     hidden_global_offset_z
      - .offset:         256
        .size:           2
        .value_kind:     hidden_grid_dims
      - .offset:         280
        .size:           8
        .value_kind:     hidden_multigrid_sync_arg
      - .offset:         312
        .size:           4
        .value_kind:     hidden_dynamic_lds_size
    .group_segment_fixed_size: 0
    .kernarg_segment_align: 8
    .kernarg_segment_size: 448
    .language:       OpenCL C
    .language_version:
      - 2
      - 0
    .max_flat_workgroup_size: 512
    .name:           _Z14fwd_megakernel6Params
    .private_segment_fixed_size: 0
    .sgpr_count:     108
    .sgpr_spill_count: 326
    .symbol:         _Z14fwd_megakernel6Params.kd
    .uniform_work_group_size: 1
    .uses_dynamic_stack: false
    .vgpr_count:     256
    .vgpr_spill_count: 0
    .wavefront_size: 64
